# baseline (speedup 1.0000x reference)
; DI unsigned pack2(float a, float b) { return (unsigned)f2bf(a) | ((unsigned)f2bf(b) << 16); }
; DI float sigmoidf_(float x) { return __builtin_amdgcn_rcpf(1.0f + __expf(-x)); }
;   DI void operator()(f32x4 (&acc)[4][4], int m0w, int n0w, int fr, int fq) const {
; #pragma unroll
;     for (int mi = 0; mi < 4; ++mi)
; #pragma unroll
;       for (int ni = 0; ni < 4; ++ni) {
;         const int col = n0w + ni * 16 + fq * 4;
;         const f32x4 bv = *(const f32x4*)(bias + col);
;         uint2 w;
;         w.x = pack2(sigmoidf_(acc[mi][ni][0] + bv[0]), sigmoidf_(acc[mi][ni][1] + bv[1]));
;         w.y = pack2(sigmoidf_(acc[mi][ni][2] + bv[2]), sigmoidf_(acc[mi][ni][3] + bv[3]));
;         *(uint2*)(G + (size_t)(m0w + mi * 16 + fr) * D + col) = w;
;       }
;   }
.LBB0_434:
	v_or_b32_e32 v140, s3, v151
	v_ashrrev_i32_e32 v141, 31, v140
	v_lshl_add_u64 v[132:133], v[140:141], 2, s[22:23]
	global_load_dwordx4 v[186:189], v[132:133], off
	global_load_dwordx4 v[190:193], v[132:133], off offset:64
	global_load_dwordx4 v[194:197], v[132:133], off offset:128
	global_load_dwordx4 v[198:201], v[132:133], off offset:192
	v_add_u32_e32 v134, s2, v152
	v_ashrrev_i32_e32 v135, 31, v134
	v_lshlrev_b64 v[142:143], 12, v[134:135]
	s_movk_i32 s2, 0x7fff
	v_readlane_b32 s0, v248, 7
	v_readlane_b32 s1, v248, 8
	s_andn2_b64 vcc, exec, s[24:25]
	s_mov_b32 s4, s36
	s_mov_b32 s5, s29
	s_waitcnt vmcnt(0)
	v_add_f32_e32 v124, v124, v186
	v_mul_f32_e32 v124, 0xbfb8aa3b, v124
	v_exp_f32_e32 v124, v124
	s_nop 0
	v_add_f32_e32 v124, 1.0, v124
	v_rcp_f32_e32 v135, v124
	v_add_f32_e32 v124, v125, v187
	v_mul_f32_e32 v124, 0xbfb8aa3b, v124
	v_exp_f32_e32 v124, v124
	s_nop 0
	v_add_f32_e32 v124, 1.0, v124
	v_rcp_f32_e32 v136, v124
	v_add_f32_e32 v124, v126, v188
	v_mul_f32_e32 v124, 0xbfb8aa3b, v124
	v_exp_f32_e32 v124, v124
	s_nop 0
	v_add_f32_e32 v124, 1.0, v124
	v_rcp_f32_e32 v137, v124
	v_add_f32_e32 v124, v127, v189
	v_mul_f32_e32 v124, 0xbfb8aa3b, v124
	v_exp_f32_e32 v124, v124
	v_and_b32_sdwa v139, v137, v217 dst_sel:DWORD dst_unused:UNUSED_PAD src0_sel:WORD_1 src1_sel:DWORD
	v_add3_u32 v137, v137, v139, s2
	v_lshl_add_u64 v[126:127], s[0:1], 0, v[142:143]
	v_add_f32_e32 v124, 1.0, v124
	v_rcp_f32_e32 v138, v124
	v_lshlrev_b64 v[124:125], 1, v[140:141]
	v_and_b32_sdwa v140, v135, v217 dst_sel:DWORD dst_unused:UNUSED_PAD src0_sel:WORD_1 src1_sel:DWORD
	v_add3_u32 v135, v135, v140, s2
	v_and_b32_sdwa v139, v138, v217 dst_sel:DWORD dst_unused:UNUSED_PAD src0_sel:WORD_1 src1_sel:DWORD
	v_and_b32_sdwa v140, v136, v217 dst_sel:DWORD dst_unused:UNUSED_PAD src0_sel:WORD_1 src1_sel:DWORD
	v_add3_u32 v138, v138, v139, s2
	v_add3_u32 v136, v136, v140, s2
	v_and_b32_e32 v138, 0xffff0000, v138
	v_and_b32_e32 v136, 0xffff0000, v136
	v_lshl_add_u64 v[126:127], v[126:127], 0, v[124:125]
	v_or_b32_sdwa v137, v138, v137 dst_sel:DWORD dst_unused:UNUSED_PAD src0_sel:DWORD src1_sel:WORD_1
	v_or_b32_sdwa v136, v136, v135 dst_sel:DWORD dst_unused:UNUSED_PAD src0_sel:DWORD src1_sel:WORD_1
	global_store_dwordx2 v[126:127], v[136:137], off
	s_nop 0
	v_add_f32_e32 v120, v120, v190
	v_add_f32_e32 v122, v122, v192
	v_mul_f32_e32 v120, 0xbfb8aa3b, v120
	v_add_f32_e32 v121, v121, v191
	v_mul_f32_e32 v122, 0xbfb8aa3b, v122
	v_add_f32_e32 v123, v123, v193
	v_exp_f32_e32 v120, v120
	v_mul_f32_e32 v121, 0xbfb8aa3b, v121
	v_exp_f32_e32 v122, v122
	v_mul_f32_e32 v123, 0xbfb8aa3b, v123
	v_exp_f32_e32 v121, v121
	v_exp_f32_e32 v123, v123
	v_add_f32_e32 v120, 1.0, v120
	v_add_f32_e32 v122, 1.0, v122
	v_rcp_f32_e32 v120, v120
	v_add_f32_e32 v121, 1.0, v121
	v_rcp_f32_e32 v122, v122
	v_add_f32_e32 v123, 1.0, v123
	v_rcp_f32_e32 v121, v121
	v_rcp_f32_e32 v123, v123
	v_and_b32_sdwa v135, v122, v217 dst_sel:DWORD dst_unused:UNUSED_PAD src0_sel:WORD_1 src1_sel:DWORD
	v_and_b32_sdwa v136, v120, v217 dst_sel:DWORD dst_unused:UNUSED_PAD src0_sel:WORD_1 src1_sel:DWORD
	v_add3_u32 v120, v120, v136, s2
	v_add3_u32 v122, v122, v135, s2
	v_and_b32_sdwa v135, v123, v217 dst_sel:DWORD dst_unused:UNUSED_PAD src0_sel:WORD_1 src1_sel:DWORD
	v_and_b32_sdwa v136, v121, v217 dst_sel:DWORD dst_unused:UNUSED_PAD src0_sel:WORD_1 src1_sel:DWORD
	v_add3_u32 v123, v123, v135, s2
	v_add3_u32 v121, v121, v136, s2
	v_and_b32_e32 v123, 0xffff0000, v123
	v_and_b32_e32 v135, 0xffff0000, v121
	v_or_b32_sdwa v121, v123, v122 dst_sel:DWORD dst_unused:UNUSED_PAD src0_sel:DWORD src1_sel:WORD_1
	v_or_b32_sdwa v120, v135, v120 dst_sel:DWORD dst_unused:UNUSED_PAD src0_sel:DWORD src1_sel:WORD_1
	global_store_dwordx2 v[126:127], v[120:121], off offset:32
	s_nop 0
	v_add_f32_e32 v116, v116, v194
	v_add_f32_e32 v118, v118, v196
	v_mul_f32_e32 v116, 0xbfb8aa3b, v116
	v_add_f32_e32 v117, v117, v195
	v_mul_f32_e32 v118, 0xbfb8aa3b, v118
	v_add_f32_e32 v119, v119, v197
	v_exp_f32_e32 v116, v116
	v_mul_f32_e32 v117, 0xbfb8aa3b, v117
	v_exp_f32_e32 v118, v118
	v_mul_f32_e32 v119, 0xbfb8aa3b, v119
	v_exp_f32_e32 v117, v117
	v_exp_f32_e32 v119, v119
	v_add_f32_e32 v116, 1.0, v116
	v_add_f32_e32 v118, 1.0, v118
	v_rcp_f32_e32 v116, v116
	v_add_f32_e32 v117, 1.0, v117
	v_rcp_f32_e32 v118, v118
	v_add_f32_e32 v119, 1.0, v119
	v_rcp_f32_e32 v117, v117
	v_rcp_f32_e32 v119, v119
	v_and_b32_sdwa v120, v118, v217 dst_sel:DWORD dst_unused:UNUSED_PAD src0_sel:WORD_1 src1_sel:DWORD
	v_and_b32_sdwa v121, v116, v217 dst_sel:DWORD dst_unused:UNUSED_PAD src0_sel:WORD_1 src1_sel:DWORD
	v_add3_u32 v116, v116, v121, s2
	v_add3_u32 v118, v118, v120, s2
	v_and_b32_sdwa v120, v119, v217 dst_sel:DWORD dst_unused:UNUSED_PAD src0_sel:WORD_1 src1_sel:DWORD
	v_and_b32_sdwa v121, v117, v217 dst_sel:DWORD dst_unused:UNUSED_PAD src0_sel:WORD_1 src1_sel:DWORD
	v_add3_u32 v119, v119, v120, s2
	v_add3_u32 v117, v117, v121, s2
	v_and_b32_e32 v119, 0xffff0000, v119
	v_and_b32_e32 v120, 0xffff0000, v117
	v_or_b32_sdwa v117, v119, v118 dst_sel:DWORD dst_unused:UNUSED_PAD src0_sel:DWORD src1_sel:WORD_1
	v_or_b32_sdwa v116, v120, v116 dst_sel:DWORD dst_unused:UNUSED_PAD src0_sel:DWORD src1_sel:WORD_1
	global_store_dwordx2 v[126:127], v[116:117], off offset:64
	s_nop 0
	v_add_f32_e32 v112, v112, v198
	v_add_f32_e32 v114, v114, v200
	v_mul_f32_e32 v112, 0xbfb8aa3b, v112
	v_add_f32_e32 v113, v113, v199
	v_mul_f32_e32 v114, 0xbfb8aa3b, v114
	v_add_f32_e32 v115, v115, v201
	v_exp_f32_e32 v112, v112
	v_mul_f32_e32 v113, 0xbfb8aa3b, v113
	v_exp_f32_e32 v114, v114
	v_mul_f32_e32 v115, 0xbfb8aa3b, v115
	v_exp_f32_e32 v113, v113
	v_exp_f32_e32 v115, v115
; DI unsigned pack2(float a, float b) { return (unsigned)f2bf(a) | ((unsigned)f2bf(b) << 16); }
; DI float sigmoidf_(float x) { return __builtin_amdgcn_rcpf(1.0f + __expf(-x)); }
;   DI void operator()(f32x4 (&acc)[4][4], int m0w, int n0w, int fr, int fq) const {
; #pragma unroll
;     for (int mi = 0; mi < 4; ++mi)
; #pragma unroll
;       for (int ni = 0; ni < 4; ++ni) {
;         const int col = n0w + ni * 16 + fq * 4;
;         const f32x4 bv = *(const f32x4*)(bias + col);
;         uint2 w;
;         w.x = pack2(sigmoidf_(acc[mi][ni][0] + bv[0]), sigmoidf_(acc[mi][ni][1] + bv[1]));
;         w.y = pack2(sigmoidf_(acc[mi][ni][2] + bv[2]), sigmoidf_(acc[mi][ni][3] + bv[3]));
;         *(uint2*)(G + (size_t)(m0w + mi * 16 + fr) * D + col) = w;
;       }
;   }
	v_add_f32_e32 v112, 1.0, v112
	v_add_f32_e32 v114, 1.0, v114
	v_rcp_f32_e32 v112, v112
	v_add_f32_e32 v113, 1.0, v113
	v_rcp_f32_e32 v114, v114
	v_add_f32_e32 v115, 1.0, v115
	v_rcp_f32_e32 v113, v113
	v_rcp_f32_e32 v115, v115
	v_and_b32_sdwa v116, v114, v217 dst_sel:DWORD dst_unused:UNUSED_PAD src0_sel:WORD_1 src1_sel:DWORD
	v_and_b32_sdwa v117, v112, v217 dst_sel:DWORD dst_unused:UNUSED_PAD src0_sel:WORD_1 src1_sel:DWORD
	v_add3_u32 v112, v112, v117, s2
	v_add3_u32 v114, v114, v116, s2
	v_and_b32_sdwa v116, v115, v217 dst_sel:DWORD dst_unused:UNUSED_PAD src0_sel:WORD_1 src1_sel:DWORD
	v_and_b32_sdwa v117, v113, v217 dst_sel:DWORD dst_unused:UNUSED_PAD src0_sel:WORD_1 src1_sel:DWORD
	v_add3_u32 v115, v115, v116, s2
	v_add3_u32 v113, v113, v117, s2
	v_and_b32_e32 v115, 0xffff0000, v115
	v_and_b32_e32 v116, 0xffff0000, v113
	v_or_b32_sdwa v113, v115, v114 dst_sel:DWORD dst_unused:UNUSED_PAD src0_sel:DWORD src1_sel:WORD_1
	v_or_b32_sdwa v112, v116, v112 dst_sel:DWORD dst_unused:UNUSED_PAD src0_sel:DWORD src1_sel:WORD_1
	global_store_dwordx2 v[126:127], v[112:113], off offset:96
	v_or_b32_e32 v112, 16, v134
	v_ashrrev_i32_e32 v113, 31, v112
	v_lshlrev_b64 v[116:117], 12, v[112:113]
	s_nop 0
	v_add_f32_e32 v108, v108, v186
	v_mul_f32_e32 v108, 0xbfb8aa3b, v108
	v_exp_f32_e32 v108, v108
	s_nop 0
	v_add_f32_e32 v108, 1.0, v108
	v_rcp_f32_e32 v112, v108
	v_add_f32_e32 v108, v109, v187
	v_mul_f32_e32 v108, 0xbfb8aa3b, v108
	v_exp_f32_e32 v108, v108
	s_nop 0
	v_add_f32_e32 v108, 1.0, v108
	v_rcp_f32_e32 v113, v108
	v_add_f32_e32 v108, v110, v188
	v_mul_f32_e32 v108, 0xbfb8aa3b, v108
	v_exp_f32_e32 v108, v108
	s_nop 0
	v_add_f32_e32 v108, 1.0, v108
	v_rcp_f32_e32 v110, v108
	v_add_f32_e32 v108, v111, v189
	v_mul_f32_e32 v108, 0xbfb8aa3b, v108
	v_exp_f32_e32 v108, v108
	v_and_b32_sdwa v114, v110, v217 dst_sel:DWORD dst_unused:UNUSED_PAD src0_sel:WORD_1 src1_sel:DWORD
	v_and_b32_sdwa v115, v112, v217 dst_sel:DWORD dst_unused:UNUSED_PAD src0_sel:WORD_1 src1_sel:DWORD
	v_add3_u32 v112, v112, v115, s2
	v_add_f32_e32 v108, 1.0, v108
	v_rcp_f32_e32 v111, v108
	v_add3_u32 v110, v110, v114, s2
	v_and_b32_sdwa v115, v113, v217 dst_sel:DWORD dst_unused:UNUSED_PAD src0_sel:WORD_1 src1_sel:DWORD
	v_add3_u32 v113, v113, v115, s2
	v_and_b32_sdwa v114, v111, v217 dst_sel:DWORD dst_unused:UNUSED_PAD src0_sel:WORD_1 src1_sel:DWORD
	v_add3_u32 v111, v111, v114, s2
	v_lshl_add_u64 v[108:109], s[0:1], 0, v[116:117]
	v_and_b32_e32 v111, 0xffff0000, v111
	v_and_b32_e32 v113, 0xffff0000, v113
	v_lshl_add_u64 v[108:109], v[108:109], 0, v[124:125]
	v_or_b32_sdwa v111, v111, v110 dst_sel:DWORD dst_unused:UNUSED_PAD src0_sel:DWORD src1_sel:WORD_1
	v_or_b32_sdwa v110, v113, v112 dst_sel:DWORD dst_unused:UNUSED_PAD src0_sel:DWORD src1_sel:WORD_1
	global_store_dwordx2 v[108:109], v[110:111], off
	s_nop 0
	v_add_f32_e32 v104, v104, v190
	v_add_f32_e32 v106, v106, v192
	v_mul_f32_e32 v104, 0xbfb8aa3b, v104
	v_add_f32_e32 v105, v105, v191
	v_mul_f32_e32 v106, 0xbfb8aa3b, v106
	v_add_f32_e32 v107, v107, v193
	v_exp_f32_e32 v104, v104
	v_mul_f32_e32 v105, 0xbfb8aa3b, v105
	v_exp_f32_e32 v106, v106
	v_mul_f32_e32 v107, 0xbfb8aa3b, v107
	v_exp_f32_e32 v105, v105
	v_exp_f32_e32 v107, v107
	v_add_f32_e32 v104, 1.0, v104
	v_add_f32_e32 v106, 1.0, v106
	v_rcp_f32_e32 v104, v104
	v_add_f32_e32 v105, 1.0, v105
	v_rcp_f32_e32 v106, v106
	v_add_f32_e32 v107, 1.0, v107
	v_rcp_f32_e32 v105, v105
	v_rcp_f32_e32 v107, v107
	v_and_b32_sdwa v110, v106, v217 dst_sel:DWORD dst_unused:UNUSED_PAD src0_sel:WORD_1 src1_sel:DWORD
	v_and_b32_sdwa v111, v104, v217 dst_sel:DWORD dst_unused:UNUSED_PAD src0_sel:WORD_1 src1_sel:DWORD
	v_add3_u32 v104, v104, v111, s2
	v_add3_u32 v106, v106, v110, s2
	v_and_b32_sdwa v110, v107, v217 dst_sel:DWORD dst_unused:UNUSED_PAD src0_sel:WORD_1 src1_sel:DWORD
	v_and_b32_sdwa v111, v105, v217 dst_sel:DWORD dst_unused:UNUSED_PAD src0_sel:WORD_1 src1_sel:DWORD
	v_add3_u32 v107, v107, v110, s2
	v_add3_u32 v105, v105, v111, s2
	v_and_b32_e32 v107, 0xffff0000, v107
	v_and_b32_e32 v110, 0xffff0000, v105
	v_or_b32_sdwa v105, v107, v106 dst_sel:DWORD dst_unused:UNUSED_PAD src0_sel:DWORD src1_sel:WORD_1
	v_or_b32_sdwa v104, v110, v104 dst_sel:DWORD dst_unused:UNUSED_PAD src0_sel:DWORD src1_sel:WORD_1
	global_store_dwordx2 v[108:109], v[104:105], off offset:32
	s_nop 0
	v_add_f32_e32 v100, v100, v194
	v_add_f32_e32 v102, v102, v196
	v_mul_f32_e32 v100, 0xbfb8aa3b, v100
	v_add_f32_e32 v101, v101, v195
	v_mul_f32_e32 v102, 0xbfb8aa3b, v102
	v_add_f32_e32 v103, v103, v197
	v_exp_f32_e32 v100, v100
	v_mul_f32_e32 v101, 0xbfb8aa3b, v101
	v_exp_f32_e32 v102, v102
	v_mul_f32_e32 v103, 0xbfb8aa3b, v103
	v_exp_f32_e32 v101, v101
	v_exp_f32_e32 v103, v103
	v_add_f32_e32 v100, 1.0, v100
	v_add_f32_e32 v102, 1.0, v102
	v_rcp_f32_e32 v100, v100
	v_add_f32_e32 v101, 1.0, v101
	v_rcp_f32_e32 v102, v102
	v_add_f32_e32 v103, 1.0, v103
	v_rcp_f32_e32 v101, v101
	v_rcp_f32_e32 v103, v103
	v_and_b32_sdwa v104, v102, v217 dst_sel:DWORD dst_unused:UNUSED_PAD src0_sel:WORD_1 src1_sel:DWORD
	v_and_b32_sdwa v105, v100, v217 dst_sel:DWORD dst_unused:UNUSED_PAD src0_sel:WORD_1 src1_sel:DWORD
	v_add3_u32 v100, v100, v105, s2
	v_add3_u32 v102, v102, v104, s2
	v_and_b32_sdwa v104, v103, v217 dst_sel:DWORD dst_unused:UNUSED_PAD src0_sel:WORD_1 src1_sel:DWORD
	v_and_b32_sdwa v105, v101, v217 dst_sel:DWORD dst_unused:UNUSED_PAD src0_sel:WORD_1 src1_sel:DWORD
	v_add3_u32 v103, v103, v104, s2
	v_add3_u32 v101, v101, v105, s2
	v_and_b32_e32 v103, 0xffff0000, v103
	v_and_b32_e32 v104, 0xffff0000, v101
	v_or_b32_sdwa v101, v103, v102 dst_sel:DWORD dst_unused:UNUSED_PAD src0_sel:DWORD src1_sel:WORD_1
; DI unsigned pack2(float a, float b) { return (unsigned)f2bf(a) | ((unsigned)f2bf(b) << 16); }
; DI float sigmoidf_(float x) { return __builtin_amdgcn_rcpf(1.0f + __expf(-x)); }
;   DI void operator()(f32x4 (&acc)[4][4], int m0w, int n0w, int fr, int fq) const {
; #pragma unroll
;     for (int mi = 0; mi < 4; ++mi)
; #pragma unroll
;       for (int ni = 0; ni < 4; ++ni) {
;         const int col = n0w + ni * 16 + fq * 4;
;         const f32x4 bv = *(const f32x4*)(bias + col);
;         uint2 w;
;         w.x = pack2(sigmoidf_(acc[mi][ni][0] + bv[0]), sigmoidf_(acc[mi][ni][1] + bv[1]));
;         w.y = pack2(sigmoidf_(acc[mi][ni][2] + bv[2]), sigmoidf_(acc[mi][ni][3] + bv[3]));
;         *(uint2*)(G + (size_t)(m0w + mi * 16 + fr) * D + col) = w;
;       }
;   }
	v_or_b32_sdwa v100, v104, v100 dst_sel:DWORD dst_unused:UNUSED_PAD src0_sel:DWORD src1_sel:WORD_1
	global_store_dwordx2 v[108:109], v[100:101], off offset:64
	s_nop 0
	v_add_f32_e32 v96, v96, v198
	v_add_f32_e32 v98, v98, v200
	v_mul_f32_e32 v96, 0xbfb8aa3b, v96
	v_add_f32_e32 v97, v97, v199
	v_mul_f32_e32 v98, 0xbfb8aa3b, v98
	v_add_f32_e32 v99, v99, v201
	v_exp_f32_e32 v96, v96
	v_mul_f32_e32 v97, 0xbfb8aa3b, v97
	v_exp_f32_e32 v98, v98
	v_mul_f32_e32 v99, 0xbfb8aa3b, v99
	v_exp_f32_e32 v97, v97
	v_exp_f32_e32 v99, v99
	v_add_f32_e32 v96, 1.0, v96
	v_add_f32_e32 v98, 1.0, v98
	v_rcp_f32_e32 v96, v96
	v_add_f32_e32 v97, 1.0, v97
	v_rcp_f32_e32 v98, v98
	v_add_f32_e32 v99, 1.0, v99
	v_rcp_f32_e32 v97, v97
	v_rcp_f32_e32 v99, v99
	v_and_b32_sdwa v100, v98, v217 dst_sel:DWORD dst_unused:UNUSED_PAD src0_sel:WORD_1 src1_sel:DWORD
	v_and_b32_sdwa v101, v96, v217 dst_sel:DWORD dst_unused:UNUSED_PAD src0_sel:WORD_1 src1_sel:DWORD
	v_add3_u32 v96, v96, v101, s2
	v_add3_u32 v98, v98, v100, s2
	v_and_b32_sdwa v100, v99, v217 dst_sel:DWORD dst_unused:UNUSED_PAD src0_sel:WORD_1 src1_sel:DWORD
	v_and_b32_sdwa v101, v97, v217 dst_sel:DWORD dst_unused:UNUSED_PAD src0_sel:WORD_1 src1_sel:DWORD
	v_add3_u32 v99, v99, v100, s2
	v_add3_u32 v97, v97, v101, s2
	v_and_b32_e32 v99, 0xffff0000, v99
	v_and_b32_e32 v100, 0xffff0000, v97
	v_or_b32_sdwa v97, v99, v98 dst_sel:DWORD dst_unused:UNUSED_PAD src0_sel:DWORD src1_sel:WORD_1
	v_or_b32_sdwa v96, v100, v96 dst_sel:DWORD dst_unused:UNUSED_PAD src0_sel:DWORD src1_sel:WORD_1
	global_store_dwordx2 v[108:109], v[96:97], off offset:96
	v_or_b32_e32 v96, 32, v134
	v_ashrrev_i32_e32 v97, 31, v96
	v_lshlrev_b64 v[100:101], 12, v[96:97]
	s_nop 0
	v_add_f32_e32 v92, v92, v186
	v_mul_f32_e32 v92, 0xbfb8aa3b, v92
	v_exp_f32_e32 v92, v92
	s_nop 0
	v_add_f32_e32 v92, 1.0, v92
	v_rcp_f32_e32 v96, v92
	v_add_f32_e32 v92, v93, v187
	v_mul_f32_e32 v92, 0xbfb8aa3b, v92
	v_exp_f32_e32 v92, v92
	s_nop 0
	v_add_f32_e32 v92, 1.0, v92
	v_rcp_f32_e32 v97, v92
	v_add_f32_e32 v92, v94, v188
	v_mul_f32_e32 v92, 0xbfb8aa3b, v92
	v_exp_f32_e32 v92, v92
	s_nop 0
	v_add_f32_e32 v92, 1.0, v92
	v_rcp_f32_e32 v94, v92
	v_add_f32_e32 v92, v95, v189
	v_mul_f32_e32 v92, 0xbfb8aa3b, v92
	v_exp_f32_e32 v92, v92
	v_and_b32_sdwa v98, v94, v217 dst_sel:DWORD dst_unused:UNUSED_PAD src0_sel:WORD_1 src1_sel:DWORD
	v_and_b32_sdwa v99, v96, v217 dst_sel:DWORD dst_unused:UNUSED_PAD src0_sel:WORD_1 src1_sel:DWORD
	v_add3_u32 v96, v96, v99, s2
	v_add_f32_e32 v92, 1.0, v92
	v_rcp_f32_e32 v95, v92
	v_add3_u32 v94, v94, v98, s2
	v_and_b32_sdwa v99, v97, v217 dst_sel:DWORD dst_unused:UNUSED_PAD src0_sel:WORD_1 src1_sel:DWORD
	v_add3_u32 v97, v97, v99, s2
	v_and_b32_sdwa v98, v95, v217 dst_sel:DWORD dst_unused:UNUSED_PAD src0_sel:WORD_1 src1_sel:DWORD
	v_add3_u32 v95, v95, v98, s2
	v_lshl_add_u64 v[92:93], s[0:1], 0, v[100:101]
	v_and_b32_e32 v95, 0xffff0000, v95
	v_and_b32_e32 v97, 0xffff0000, v97
	v_lshl_add_u64 v[92:93], v[92:93], 0, v[124:125]
	v_or_b32_sdwa v95, v95, v94 dst_sel:DWORD dst_unused:UNUSED_PAD src0_sel:DWORD src1_sel:WORD_1
	v_or_b32_sdwa v94, v97, v96 dst_sel:DWORD dst_unused:UNUSED_PAD src0_sel:DWORD src1_sel:WORD_1
	global_store_dwordx2 v[92:93], v[94:95], off
	s_nop 0
	v_add_f32_e32 v88, v88, v190
	v_add_f32_e32 v90, v90, v192
	v_mul_f32_e32 v88, 0xbfb8aa3b, v88
	v_add_f32_e32 v89, v89, v191
	v_mul_f32_e32 v90, 0xbfb8aa3b, v90
	v_add_f32_e32 v91, v91, v193
	v_exp_f32_e32 v88, v88
	v_mul_f32_e32 v89, 0xbfb8aa3b, v89
	v_exp_f32_e32 v90, v90
	v_mul_f32_e32 v91, 0xbfb8aa3b, v91
	v_exp_f32_e32 v89, v89
	v_exp_f32_e32 v91, v91
	v_add_f32_e32 v88, 1.0, v88
	v_add_f32_e32 v90, 1.0, v90
	v_rcp_f32_e32 v88, v88
	v_add_f32_e32 v89, 1.0, v89
	v_rcp_f32_e32 v90, v90
	v_add_f32_e32 v91, 1.0, v91
	v_rcp_f32_e32 v89, v89
	v_rcp_f32_e32 v91, v91
	v_and_b32_sdwa v94, v90, v217 dst_sel:DWORD dst_unused:UNUSED_PAD src0_sel:WORD_1 src1_sel:DWORD
	v_and_b32_sdwa v95, v88, v217 dst_sel:DWORD dst_unused:UNUSED_PAD src0_sel:WORD_1 src1_sel:DWORD
	v_add3_u32 v88, v88, v95, s2
	v_add3_u32 v90, v90, v94, s2
	v_and_b32_sdwa v94, v91, v217 dst_sel:DWORD dst_unused:UNUSED_PAD src0_sel:WORD_1 src1_sel:DWORD
	v_and_b32_sdwa v95, v89, v217 dst_sel:DWORD dst_unused:UNUSED_PAD src0_sel:WORD_1 src1_sel:DWORD
	v_add3_u32 v91, v91, v94, s2
	v_add3_u32 v89, v89, v95, s2
	v_and_b32_e32 v91, 0xffff0000, v91
	v_and_b32_e32 v94, 0xffff0000, v89
	v_or_b32_sdwa v89, v91, v90 dst_sel:DWORD dst_unused:UNUSED_PAD src0_sel:DWORD src1_sel:WORD_1
	v_or_b32_sdwa v88, v94, v88 dst_sel:DWORD dst_unused:UNUSED_PAD src0_sel:DWORD src1_sel:WORD_1
	global_store_dwordx2 v[92:93], v[88:89], off offset:32
	s_nop 0
	v_add_f32_e32 v84, v84, v194
	v_add_f32_e32 v86, v86, v196
	v_mul_f32_e32 v84, 0xbfb8aa3b, v84
	v_add_f32_e32 v85, v85, v195
	v_mul_f32_e32 v86, 0xbfb8aa3b, v86
	v_add_f32_e32 v87, v87, v197
	v_exp_f32_e32 v84, v84
	v_mul_f32_e32 v85, 0xbfb8aa3b, v85
	v_exp_f32_e32 v86, v86
	v_mul_f32_e32 v87, 0xbfb8aa3b, v87
	v_exp_f32_e32 v85, v85
	v_exp_f32_e32 v87, v87
	v_add_f32_e32 v84, 1.0, v84
	v_add_f32_e32 v86, 1.0, v86
	v_rcp_f32_e32 v84, v84
	v_add_f32_e32 v85, 1.0, v85
	v_rcp_f32_e32 v86, v86
	v_add_f32_e32 v87, 1.0, v87
	v_rcp_f32_e32 v85, v85
	v_rcp_f32_e32 v87, v87
	v_and_b32_sdwa v88, v86, v217 dst_sel:DWORD dst_unused:UNUSED_PAD src0_sel:WORD_1 src1_sel:DWORD
	v_and_b32_sdwa v89, v84, v217 dst_sel:DWORD dst_unused:UNUSED_PAD src0_sel:WORD_1 src1_sel:DWORD
	v_add3_u32 v84, v84, v89, s2
	v_add3_u32 v86, v86, v88, s2
	v_and_b32_sdwa v88, v87, v217 dst_sel:DWORD dst_unused:UNUSED_PAD src0_sel:WORD_1 src1_sel:DWORD
	v_and_b32_sdwa v89, v85, v217 dst_sel:DWORD dst_unused:UNUSED_PAD src0_sel:WORD_1 src1_sel:DWORD
; DI unsigned pack2(float a, float b) { return (unsigned)f2bf(a) | ((unsigned)f2bf(b) << 16); }
; DI float sigmoidf_(float x) { return __builtin_amdgcn_rcpf(1.0f + __expf(-x)); }
;   DI void operator()(f32x4 (&acc)[4][4], int m0w, int n0w, int fr, int fq) const {
;     ...
;       for (int ni = 0; ni < 4; ++ni) {
;         const int col = n0w + ni * 16 + fq * 4;
;         const f32x4 bv = *(const f32x4*)(bias + col);
;         uint2 w;
;         w.x = pack2(sigmoidf_(acc[mi][ni][0] + bv[0]), sigmoidf_(acc[mi][ni][1] + bv[1]));
;         w.y = pack2(sigmoidf_(acc[mi][ni][2] + bv[2]), sigmoidf_(acc[mi][ni][3] + bv[3]));
;         *(uint2*)(G + (size_t)(m0w + mi * 16 + fr) * D + col) = w;
	v_add3_u32 v87, v87, v88, s2
	v_add3_u32 v85, v85, v89, s2
	v_and_b32_e32 v87, 0xffff0000, v87
	v_and_b32_e32 v88, 0xffff0000, v85
	v_or_b32_sdwa v85, v87, v86 dst_sel:DWORD dst_unused:UNUSED_PAD src0_sel:DWORD src1_sel:WORD_1
	v_or_b32_sdwa v84, v88, v84 dst_sel:DWORD dst_unused:UNUSED_PAD src0_sel:DWORD src1_sel:WORD_1
	global_store_dwordx2 v[92:93], v[84:85], off offset:64
	s_nop 0
	v_add_f32_e32 v80, v80, v198
	v_add_f32_e32 v82, v82, v200
	v_mul_f32_e32 v80, 0xbfb8aa3b, v80
	v_add_f32_e32 v81, v81, v199
	v_mul_f32_e32 v82, 0xbfb8aa3b, v82
	v_add_f32_e32 v83, v83, v201
	v_exp_f32_e32 v80, v80
	v_mul_f32_e32 v81, 0xbfb8aa3b, v81
	v_exp_f32_e32 v82, v82
	v_mul_f32_e32 v83, 0xbfb8aa3b, v83
	v_exp_f32_e32 v81, v81
	v_exp_f32_e32 v83, v83
	v_add_f32_e32 v80, 1.0, v80
	v_add_f32_e32 v82, 1.0, v82
	v_rcp_f32_e32 v80, v80
	v_add_f32_e32 v81, 1.0, v81
	v_rcp_f32_e32 v82, v82
	v_add_f32_e32 v83, 1.0, v83
	v_rcp_f32_e32 v81, v81
	v_rcp_f32_e32 v83, v83
	v_and_b32_sdwa v84, v82, v217 dst_sel:DWORD dst_unused:UNUSED_PAD src0_sel:WORD_1 src1_sel:DWORD
	v_and_b32_sdwa v85, v80, v217 dst_sel:DWORD dst_unused:UNUSED_PAD src0_sel:WORD_1 src1_sel:DWORD
	v_add3_u32 v80, v80, v85, s2
	v_add3_u32 v82, v82, v84, s2
	v_and_b32_sdwa v84, v83, v217 dst_sel:DWORD dst_unused:UNUSED_PAD src0_sel:WORD_1 src1_sel:DWORD
	v_and_b32_sdwa v85, v81, v217 dst_sel:DWORD dst_unused:UNUSED_PAD src0_sel:WORD_1 src1_sel:DWORD
	v_add3_u32 v83, v83, v84, s2
	v_add3_u32 v81, v81, v85, s2
	v_and_b32_e32 v83, 0xffff0000, v83
	v_and_b32_e32 v84, 0xffff0000, v81
	v_or_b32_sdwa v81, v83, v82 dst_sel:DWORD dst_unused:UNUSED_PAD src0_sel:DWORD src1_sel:WORD_1
	v_or_b32_sdwa v80, v84, v80 dst_sel:DWORD dst_unused:UNUSED_PAD src0_sel:DWORD src1_sel:WORD_1
	global_store_dwordx2 v[92:93], v[80:81], off offset:96
	v_or_b32_e32 v80, 48, v134
	v_ashrrev_i32_e32 v81, 31, v80
	v_lshlrev_b64 v[84:85], 12, v[80:81]
	s_nop 0
	v_add_f32_e32 v76, v76, v186
	v_mul_f32_e32 v76, 0xbfb8aa3b, v76
	v_exp_f32_e32 v76, v76
	s_nop 0
	v_add_f32_e32 v76, 1.0, v76
	v_rcp_f32_e32 v80, v76
	v_add_f32_e32 v76, v77, v187
	v_mul_f32_e32 v76, 0xbfb8aa3b, v76
	v_exp_f32_e32 v76, v76
	s_nop 0
	v_add_f32_e32 v76, 1.0, v76
	v_rcp_f32_e32 v81, v76
	v_add_f32_e32 v76, v78, v188
	v_mul_f32_e32 v76, 0xbfb8aa3b, v76
	v_exp_f32_e32 v76, v76
	s_nop 0
	v_add_f32_e32 v76, 1.0, v76
	v_rcp_f32_e32 v78, v76
	v_add_f32_e32 v76, v79, v189
	v_mul_f32_e32 v76, 0xbfb8aa3b, v76
	v_exp_f32_e32 v76, v76
	v_and_b32_sdwa v82, v78, v217 dst_sel:DWORD dst_unused:UNUSED_PAD src0_sel:WORD_1 src1_sel:DWORD
	v_and_b32_sdwa v83, v80, v217 dst_sel:DWORD dst_unused:UNUSED_PAD src0_sel:WORD_1 src1_sel:DWORD
	v_add3_u32 v80, v80, v83, s2
	v_add_f32_e32 v76, 1.0, v76
	v_rcp_f32_e32 v79, v76
	v_add3_u32 v78, v78, v82, s2
	v_and_b32_sdwa v83, v81, v217 dst_sel:DWORD dst_unused:UNUSED_PAD src0_sel:WORD_1 src1_sel:DWORD
	v_add3_u32 v81, v81, v83, s2
	v_and_b32_sdwa v82, v79, v217 dst_sel:DWORD dst_unused:UNUSED_PAD src0_sel:WORD_1 src1_sel:DWORD
	v_add3_u32 v79, v79, v82, s2
	v_lshl_add_u64 v[76:77], s[0:1], 0, v[84:85]
	v_and_b32_e32 v79, 0xffff0000, v79
	v_and_b32_e32 v81, 0xffff0000, v81
	v_lshl_add_u64 v[76:77], v[76:77], 0, v[124:125]
	v_or_b32_sdwa v79, v79, v78 dst_sel:DWORD dst_unused:UNUSED_PAD src0_sel:DWORD src1_sel:WORD_1
	v_or_b32_sdwa v78, v81, v80 dst_sel:DWORD dst_unused:UNUSED_PAD src0_sel:DWORD src1_sel:WORD_1
	global_store_dwordx2 v[76:77], v[78:79], off
	s_mov_b64 s[0:1], -1
	s_nop 0
	v_add_f32_e32 v72, v72, v190
	v_add_f32_e32 v74, v74, v192
	v_mul_f32_e32 v72, 0xbfb8aa3b, v72
	v_add_f32_e32 v73, v73, v191
	v_mul_f32_e32 v74, 0xbfb8aa3b, v74
	v_add_f32_e32 v75, v75, v193
	v_exp_f32_e32 v72, v72
	v_mul_f32_e32 v73, 0xbfb8aa3b, v73
	v_exp_f32_e32 v74, v74
	v_mul_f32_e32 v75, 0xbfb8aa3b, v75
	v_exp_f32_e32 v73, v73
	v_exp_f32_e32 v75, v75
	v_add_f32_e32 v72, 1.0, v72
	v_add_f32_e32 v74, 1.0, v74
; DI unsigned pack2(float a, float b) { return (unsigned)f2bf(a) | ((unsigned)f2bf(b) << 16); }
; DI float sigmoidf_(float x) { return __builtin_amdgcn_rcpf(1.0f + __expf(-x)); }
;   DI void operator()(f32x4 (&acc)[4][4], int m0w, int n0w, int fr, int fq) const {
;     ...
;       for (int ni = 0; ni < 4; ++ni) {
;         const int col = n0w + ni * 16 + fq * 4;
;         const f32x4 bv = *(const f32x4*)(bias + col);
;         uint2 w;
;         w.x = pack2(sigmoidf_(acc[mi][ni][0] + bv[0]), sigmoidf_(acc[mi][ni][1] + bv[1]));
;         w.y = pack2(sigmoidf_(acc[mi][ni][2] + bv[2]), sigmoidf_(acc[mi][ni][3] + bv[3]));
;         *(uint2*)(G + (size_t)(m0w + mi * 16 + fr) * D + col) = w;
	v_rcp_f32_e32 v72, v72
	v_add_f32_e32 v73, 1.0, v73
	v_rcp_f32_e32 v74, v74
	v_add_f32_e32 v75, 1.0, v75
	v_rcp_f32_e32 v73, v73
	v_rcp_f32_e32 v75, v75
	v_and_b32_sdwa v78, v74, v217 dst_sel:DWORD dst_unused:UNUSED_PAD src0_sel:WORD_1 src1_sel:DWORD
	v_and_b32_sdwa v79, v72, v217 dst_sel:DWORD dst_unused:UNUSED_PAD src0_sel:WORD_1 src1_sel:DWORD
	v_add3_u32 v72, v72, v79, s2
	v_add3_u32 v74, v74, v78, s2
	v_and_b32_sdwa v78, v75, v217 dst_sel:DWORD dst_unused:UNUSED_PAD src0_sel:WORD_1 src1_sel:DWORD
	v_and_b32_sdwa v79, v73, v217 dst_sel:DWORD dst_unused:UNUSED_PAD src0_sel:WORD_1 src1_sel:DWORD
	v_add3_u32 v75, v75, v78, s2
	v_add3_u32 v73, v73, v79, s2
	v_and_b32_e32 v75, 0xffff0000, v75
	v_and_b32_e32 v78, 0xffff0000, v73
	v_or_b32_sdwa v73, v75, v74 dst_sel:DWORD dst_unused:UNUSED_PAD src0_sel:DWORD src1_sel:WORD_1
	v_or_b32_sdwa v72, v78, v72 dst_sel:DWORD dst_unused:UNUSED_PAD src0_sel:DWORD src1_sel:WORD_1
	global_store_dwordx2 v[76:77], v[72:73], off offset:32
	s_nop 0
	v_add_f32_e32 v68, v68, v194
	v_add_f32_e32 v70, v70, v196
	v_mul_f32_e32 v68, 0xbfb8aa3b, v68
	v_add_f32_e32 v69, v69, v195
	v_mul_f32_e32 v70, 0xbfb8aa3b, v70
	v_add_f32_e32 v71, v71, v197
	v_exp_f32_e32 v68, v68
	v_mul_f32_e32 v69, 0xbfb8aa3b, v69
	v_exp_f32_e32 v70, v70
	v_mul_f32_e32 v71, 0xbfb8aa3b, v71
	v_exp_f32_e32 v69, v69
	v_exp_f32_e32 v71, v71
	v_add_f32_e32 v68, 1.0, v68
	v_add_f32_e32 v70, 1.0, v70
	v_rcp_f32_e32 v68, v68
	v_add_f32_e32 v69, 1.0, v69
	v_rcp_f32_e32 v70, v70
	v_add_f32_e32 v71, 1.0, v71
	v_rcp_f32_e32 v69, v69
	v_rcp_f32_e32 v71, v71
	v_and_b32_sdwa v72, v70, v217 dst_sel:DWORD dst_unused:UNUSED_PAD src0_sel:WORD_1 src1_sel:DWORD
	v_and_b32_sdwa v73, v68, v217 dst_sel:DWORD dst_unused:UNUSED_PAD src0_sel:WORD_1 src1_sel:DWORD
	v_add3_u32 v68, v68, v73, s2
	v_add3_u32 v70, v70, v72, s2
	v_and_b32_sdwa v72, v71, v217 dst_sel:DWORD dst_unused:UNUSED_PAD src0_sel:WORD_1 src1_sel:DWORD
	v_and_b32_sdwa v73, v69, v217 dst_sel:DWORD dst_unused:UNUSED_PAD src0_sel:WORD_1 src1_sel:DWORD
	v_add3_u32 v71, v71, v72, s2
	v_add3_u32 v69, v69, v73, s2
	v_and_b32_e32 v71, 0xffff0000, v71
	v_and_b32_e32 v72, 0xffff0000, v69
	v_or_b32_sdwa v69, v71, v70 dst_sel:DWORD dst_unused:UNUSED_PAD src0_sel:DWORD src1_sel:WORD_1
	v_or_b32_sdwa v68, v72, v68 dst_sel:DWORD dst_unused:UNUSED_PAD src0_sel:DWORD src1_sel:WORD_1
	global_store_dwordx2 v[76:77], v[68:69], off offset:64
	s_nop 0
	v_add_f32_e32 v64, v64, v198
	v_add_f32_e32 v66, v66, v200
	v_mul_f32_e32 v64, 0xbfb8aa3b, v64
	v_add_f32_e32 v65, v65, v199
	v_mul_f32_e32 v66, 0xbfb8aa3b, v66
	v_add_f32_e32 v67, v67, v201
	v_exp_f32_e32 v64, v64
	v_mul_f32_e32 v65, 0xbfb8aa3b, v65
	v_exp_f32_e32 v66, v66
	v_mul_f32_e32 v67, 0xbfb8aa3b, v67
	v_exp_f32_e32 v65, v65
	v_exp_f32_e32 v67, v67
	v_add_f32_e32 v64, 1.0, v64
	v_add_f32_e32 v66, 1.0, v66
	v_rcp_f32_e32 v64, v64
	v_add_f32_e32 v65, 1.0, v65
	v_rcp_f32_e32 v66, v66
	v_add_f32_e32 v67, 1.0, v67
	v_rcp_f32_e32 v65, v65
	v_rcp_f32_e32 v67, v67
	v_and_b32_sdwa v68, v66, v217 dst_sel:DWORD dst_unused:UNUSED_PAD src0_sel:WORD_1 src1_sel:DWORD
	v_and_b32_sdwa v69, v64, v217 dst_sel:DWORD dst_unused:UNUSED_PAD src0_sel:WORD_1 src1_sel:DWORD
	v_add3_u32 v64, v64, v69, s2
	v_add3_u32 v66, v66, v68, s2
	v_and_b32_sdwa v68, v67, v217 dst_sel:DWORD dst_unused:UNUSED_PAD src0_sel:WORD_1 src1_sel:DWORD
	v_and_b32_sdwa v69, v65, v217 dst_sel:DWORD dst_unused:UNUSED_PAD src0_sel:WORD_1 src1_sel:DWORD
	v_add3_u32 v67, v67, v68, s2
	v_add3_u32 v65, v65, v69, s2
	v_and_b32_e32 v67, 0xffff0000, v67
	v_and_b32_e32 v68, 0xffff0000, v65
	v_or_b32_sdwa v65, v67, v66 dst_sel:DWORD dst_unused:UNUSED_PAD src0_sel:DWORD src1_sel:WORD_1
	v_or_b32_sdwa v64, v68, v64 dst_sel:DWORD dst_unused:UNUSED_PAD src0_sel:DWORD src1_sel:WORD_1
	global_store_dwordx2 v[76:77], v[64:65], off offset:96
	s_cbranch_vccz .LBB0_448
